# residual-init row loop: 6-step wave sum (ds_bpermute lane^1..32) -> DPP quad_perm/row_half_mirror/row_mirror + permlane16/32 swaps; rwkv_gn lane^1/^2 steps -> DPP quad_perm
# baseline (speedup 1.0000x reference)
; __device__ __forceinline__ void rwkv_gn(bf16* OFb, const bf16* OBb, const bf16* Vb, const float* beta, const float* gnw, const float* gnb, int tid) {
;     ...
;         float y[16], v[16]; float sm = 0.f;
; #pragma unroll
;         for (int h = 0; h < 2; ++h) { const u32x4_t a = *(const u32x4_t*)(OFb + off + 8 * h), b = *(const u32x4_t*)(OBb + off + 8 * h), vv = *(const u32x4_t*)(Vb + off + 8 * h);
;             const unsigned aw[4] = {a.x, a.y, a.z, a.w}, bw[4] = {b.x, b.y, b.z, b.w}, vw[4] = {vv.x, vv.y, vv.z, vv.w};
; #pragma unroll
;             for (int q = 0; q < 4; ++q) { y[8 * h + 2 * q] = __uint_as_float(aw[q] << 16) + __uint_as_float(bw[q] << 16); y[8 * h + 2 * q + 1] = __uint_as_float(aw[q] & 0xffff0000u) + __uint_as_float(bw[q] & 0xffff0000u);
;                 v[8 * h + 2 * q] = __uint_as_float(vw[q] << 16); v[8 * h + 2 * q + 1] = __uint_as_float(vw[q] & 0xffff0000u); } }
; #pragma unroll
;         for (int i = 0; i < 16; ++i) sm += y[i];
;         sm += __shfl_xor(sm, 1); sm += __shfl_xor(sm, 2);
.LBB0_120:
	v_lshl_add_u64 v[2:3], s[6:7], 0, v[26:27]
	s_mov_b64 s[10:11], 0x5900000
	v_add_co_u32_e32 v28, vcc, 0x5900000, v2
	v_lshl_add_u64 v[4:5], v[2:3], 0, s[10:11]
	s_nop 0
	v_addc_co_u32_e32 v29, vcc, 0, v3, vcc
	global_load_dwordx4 v[6:9], v[28:29], off
	global_load_dwordx4 v[34:37], v[4:5], off offset:16
	v_add_co_u32_e32 v4, vcc, 0x7980000, v2
	v_lshl_add_u64 v[14:15], v[2:3], 0, s[20:21]
	s_nop 0
	v_addc_co_u32_e32 v5, vcc, 0, v3, vcc
	global_load_dwordx4 v[10:13], v[4:5], off
	global_load_dwordx4 v[42:45], v[14:15], off offset:16
	s_mov_b64 s[10:11], 0xdb00000
	v_lshl_add_u64 v[30:31], v[2:3], 0, s[10:11]
	v_add_co_u32_e32 v2, vcc, 0xdb00000, v2
	s_mov_b32 s2, 0x100000
	s_nop 0
	v_addc_co_u32_e32 v3, vcc, 0, v3, vcc
	global_load_dwordx4 v[14:17], v[2:3], off
	s_nop 0
	global_load_dwordx4 v[2:5], v[30:31], off offset:16
	v_add_u32_e32 v18, s80, v18
	v_lshl_add_u64 v[26:27], v[26:27], 0, s[18:19]
	s_waitcnt vmcnt(5)
	v_lshlrev_b32_e32 v78, 16, v6
	s_waitcnt vmcnt(4)
	v_and_b32_e32 v30, 0xffff0000, v34
	v_lshlrev_b32_e32 v31, 16, v34
	v_and_b32_e32 v79, 0xffff0000, v6
	s_waitcnt vmcnt(3)
	v_lshlrev_b32_e32 v6, 16, v10
	s_waitcnt vmcnt(2)
	v_and_b32_e32 v32, 0xffff0000, v42
	v_lshlrev_b32_e32 v33, 16, v42
	v_pk_add_f32 v[30:31], v[30:31], v[32:33]
	v_and_b32_e32 v32, 0xffff0000, v35
	v_lshlrev_b32_e32 v33, 16, v35
	v_and_b32_e32 v34, 0xffff0000, v43
	v_lshlrev_b32_e32 v35, 16, v43
	v_pk_add_f32 v[32:33], v[32:33], v[34:35]
	v_and_b32_e32 v34, 0xffff0000, v36
	v_lshlrev_b32_e32 v35, 16, v36
	v_and_b32_e32 v38, 0xffff0000, v44
	v_lshlrev_b32_e32 v39, 16, v44
	v_pk_add_f32 v[34:35], v[34:35], v[38:39]
	v_and_b32_e32 v36, 0xffff0000, v37
	v_lshlrev_b32_e32 v37, 16, v37
	v_and_b32_e32 v38, 0xffff0000, v45
	v_lshlrev_b32_e32 v39, 16, v45
	v_pk_add_f32 v[36:37], v[36:37], v[38:39]
	v_lshl_add_u64 v[38:39], s[6:7], 0, v[24:25]
	v_add_co_u32_e32 v42, vcc, s2, v38
	s_mov_b32 s2, 0x204000
	s_nop 0
	v_addc_co_u32_e32 v43, vcc, 0, v39, vcc
	v_add_co_u32_e32 v38, vcc, s2, v38
	global_load_dword v0, v[42:43], off
	s_nop 0
	v_addc_co_u32_e32 v39, vcc, 0, v39, vcc
	global_load_dword v19, v[38:39], off
	v_lshlrev_b32_e32 v38, 16, v9
	v_and_b32_e32 v39, 0xffff0000, v9
	v_lshlrev_b32_e32 v42, 16, v13
	v_and_b32_e32 v43, 0xffff0000, v13
	v_pk_add_f32 v[74:75], v[38:39], v[42:43]
	v_lshlrev_b32_e32 v42, 16, v8
	v_and_b32_e32 v43, 0xffff0000, v8
	v_lshlrev_b32_e32 v8, 16, v12
	v_and_b32_e32 v9, 0xffff0000, v12
	v_pk_add_f32 v[12:13], v[42:43], v[8:9]
	global_load_dwordx4 v[42:45], v[20:21], off offset:48
	global_load_dwordx4 v[46:49], v[20:21], off offset:32
	global_load_dwordx4 v[50:53], v[20:21], off offset:16
	global_load_dwordx4 v[54:57], v[20:21], off
	global_load_dwordx4 v[58:61], v[22:23], off offset:48
	global_load_dwordx4 v[62:65], v[22:23], off offset:32
	global_load_dwordx4 v[66:69], v[22:23], off offset:16
	global_load_dwordx4 v[70:73], v[22:23], off
	s_waitcnt vmcnt(11)
	v_lshlrev_b32_e32 v38, 16, v17
	v_and_b32_e32 v39, 0xffff0000, v17
	v_lshlrev_b32_e32 v8, 16, v16
	v_and_b32_e32 v9, 0xffff0000, v16
	v_lshlrev_b32_e32 v16, 16, v7
	v_and_b32_e32 v17, 0xffff0000, v7
	v_and_b32_e32 v7, 0xffff0000, v10
	v_pk_add_f32 v[6:7], v[78:79], v[6:7]
	v_lshlrev_b32_e32 v76, 16, v11
	v_and_b32_e32 v77, 0xffff0000, v11
	v_lshlrev_b32_e32 v10, 16, v14
	v_and_b32_e32 v11, 0xffff0000, v14
	v_add_f32_e32 v14, 0, v6
	v_pk_add_f32 v[16:17], v[16:17], v[76:77]
	v_add_f32_e32 v14, v7, v14
	v_add_f32_e32 v14, v16, v14
	v_add_f32_e32 v14, v17, v14
	v_add_f32_e32 v14, v12, v14
	v_add_f32_e32 v14, v13, v14
	v_add_f32_e32 v14, v74, v14
	v_add_f32_e32 v14, v75, v14
	v_add_f32_e32 v14, v31, v14
	v_add_f32_e32 v14, v30, v14
	v_add_f32_e32 v14, v33, v14
	v_add_f32_e32 v14, v32, v14
	v_add_f32_e32 v14, v35, v14
	v_add_f32_e32 v14, v34, v14
	v_add_f32_e32 v14, v37, v14
	v_add_f32_e32 v14, v36, v14
	v_lshlrev_b32_e32 v76, 16, v15
	v_and_b32_e32 v77, 0xffff0000, v15
	s_nop 1
	v_mov_b32_dpp v15, v14 quad_perm:[1,0,3,2] row_mask:0xf bank_mask:0xf
	s_waitcnt vmcnt(10)
	v_lshlrev_b32_e32 v90, 16, v3
	v_and_b32_e32 v91, 0xffff0000, v3
	v_lshlrev_b32_e32 v94, 16, v2
	v_and_b32_e32 v95, 0xffff0000, v2
	s_waitcnt lgkmcnt(0)
	v_add_f32_e32 v14, v14, v15
	s_nop 1
	v_mov_b32_dpp v15, v14 quad_perm:[2,3,0,1] row_mask:0xf bank_mask:0xf
	v_lshl_add_u64 v[24:25], v[24:25], 0, s[12:13]
	s_waitcnt lgkmcnt(0)
; __device__ __forceinline__ unsigned pk2(float lo, float hi) { const f32x2_cv v = {lo, hi}; const bf16x2_cv b = __builtin_convertvector(v, bf16x2_cv); return __builtin_bit_cast(unsigned, b); }
; __device__ __forceinline__ void rwkv_gn(bf16* OFb, const bf16* OBb, const bf16* Vb, const float* beta, const float* gnw, const float* gnb, int tid) {
;     ...
;         const float mean = sm * (1.0f / 64.0f); float sv = 0.f;
; #pragma unroll
;         for (int i = 0; i < 16; ++i) { const float dd = y[i] - mean; sv += dd * dd; }
;         sv += __shfl_xor(sv, 1); sv += __shfl_xor(sv, 2);
;         const float rs = rsqrtf(sv * (1.0f / 64.0f) + 64e-5f);
;         const float bt = beta[(size_t)r * 16 + head] + beta[((size_t)SLAB + r) * 16 + head];
;         float res[16];
; #pragma unroll
;         for (int i = 0; i < 16; ++i) res[i] = (y[i] - mean) * rs * gnw[16 * lane + i] + gnb[16 * lane + i] + bt * v[i];
; #pragma unroll
;         for (int h = 0; h < 2; ++h) { u32x4_t w; w.x = pk2(res[8 * h], res[8 * h + 1]); w.y = pk2(res[8 * h + 2], res[8 * h + 3]); w.z = pk2(res[8 * h + 4], res[8 * h + 5]); w.w = pk2(res[8 * h + 6], res[8 * h + 7]);
;             *(u32x4_t*)(OFb + off + 8 * h) = w; }
	v_add_f32_e32 v14, v14, v15
	v_mul_f32_e32 v14, 0x3c800000, v14
	v_pk_add_f32 v[6:7], v[6:7], v[14:15] op_sel_hi:[1,0] neg_lo:[0,1] neg_hi:[0,1]
	v_pk_add_f32 v[16:17], v[16:17], v[14:15] op_sel_hi:[1,0] neg_lo:[0,1] neg_hi:[0,1]
	v_pk_mul_f32 v[78:79], v[6:7], v[6:7]
	v_pk_mul_f32 v[80:81], v[16:17], v[16:17]
	v_pk_add_f32 v[12:13], v[12:13], v[14:15] op_sel_hi:[1,0] neg_lo:[0,1] neg_hi:[0,1]
	v_pk_add_f32 v[74:75], v[74:75], v[14:15] op_sel_hi:[1,0] neg_lo:[0,1] neg_hi:[0,1]
	v_pk_mul_f32 v[82:83], v[12:13], v[12:13]
	v_pk_mul_f32 v[84:85], v[74:75], v[74:75]
	v_pk_add_f32 v[2:3], v[30:31], v[14:15] op_sel_hi:[1,0] neg_lo:[0,1] neg_hi:[0,1]
	v_pk_add_f32 v[34:35], v[34:35], v[14:15] op_sel_hi:[1,0] neg_lo:[0,1] neg_hi:[0,1]
	v_pk_add_f32 v[36:37], v[36:37], v[14:15] op_sel_hi:[1,0] neg_lo:[0,1] neg_hi:[0,1]
	v_pk_add_f32 v[32:33], v[32:33], v[14:15] op_sel_hi:[1,0] neg_lo:[0,1] neg_hi:[0,1]
	v_pk_mul_f32 v[14:15], v[2:3], v[2:3]
	v_pk_mul_f32 v[92:93], v[32:33], v[32:33]
	v_pk_mul_f32 v[86:87], v[34:35], v[34:35]
	v_pk_mul_f32 v[88:89], v[36:37], v[36:37]
	s_waitcnt vmcnt(8)
	v_add_f32_e32 v0, v0, v19
	v_add_f32_e32 v19, v78, v79
	v_add_f32_e32 v19, v80, v19
	v_add_f32_e32 v19, v81, v19
	v_add_f32_e32 v19, v82, v19
	v_add_f32_e32 v19, v83, v19
	v_add_f32_e32 v19, v84, v19
	v_add_f32_e32 v19, v85, v19
	v_add_f32_e32 v15, v15, v19
	v_add_f32_e32 v14, v14, v15
	v_add_f32_e32 v14, v93, v14
	v_add_f32_e32 v14, v92, v14
	v_add_f32_e32 v14, v87, v14
	v_add_f32_e32 v14, v86, v14
	v_add_f32_e32 v14, v89, v14
	v_add_f32_e32 v14, v88, v14
	s_nop 1
	v_mov_b32_dpp v15, v14 quad_perm:[1,0,3,2] row_mask:0xf bank_mask:0xf
	s_waitcnt lgkmcnt(0)
	v_add_f32_e32 v14, v14, v15
	s_nop 1
	v_mov_b32_dpp v15, v14 quad_perm:[2,3,0,1] row_mask:0xf bank_mask:0xf
	s_waitcnt lgkmcnt(0)
	v_add_f32_e32 v14, v14, v15
	v_mov_b32_e32 v15, 0x3a27c5ac
	v_fmamk_f32 v14, v14, 0x3c800000, v15
	v_cmp_gt_f32_e32 vcc, s33, v14
	v_mul_f32_e32 v15, 0x4b800000, v14
	s_nop 0
	v_cndmask_b32_e32 v14, v14, v15, vcc
	v_rsq_f32_e32 v14, v14
	s_nop 0
	v_mul_f32_e32 v15, 0x45800000, v14
	v_cndmask_b32_e32 v14, v14, v15, vcc
	v_pk_mul_f32 v[6:7], v[6:7], v[14:15] op_sel_hi:[1,0]
	v_pk_mul_f32 v[2:3], v[2:3], v[14:15] op_sel_hi:[1,0]
	s_waitcnt vmcnt(0)
	v_pk_fma_f32 v[6:7], v[54:55], v[6:7], v[70:71]
	v_pk_fma_f32 v[2:3], v[46:47], v[2:3], v[62:63] op_sel:[0,1,0] op_sel_hi:[1,0,1]
	v_pk_fma_f32 v[6:7], v[0:1], v[10:11], v[6:7] op_sel_hi:[0,1,1]
	v_pk_mul_f32 v[10:11], v[16:17], v[14:15] op_sel_hi:[1,0]
	v_pk_mul_f32 v[12:13], v[12:13], v[14:15] op_sel_hi:[1,0]
	v_pk_fma_f32 v[16:17], v[0:1], v[94:95], v[2:3] op_sel_hi:[0,1,1]
	v_pk_mul_f32 v[2:3], v[32:33], v[14:15] op_sel_hi:[1,0]
	v_pk_fma_f32 v[12:13], v[50:51], v[12:13], v[66:67]
	v_pk_fma_f32 v[2:3], v[48:49], v[2:3], v[64:65] op_sel:[0,1,0] op_sel_hi:[1,0,1]
	v_pk_mul_f32 v[32:33], v[34:35], v[14:15] op_sel_hi:[1,0]
	v_pk_fma_f32 v[8:9], v[0:1], v[8:9], v[12:13] op_sel_hi:[0,1,1]
	v_pk_mul_f32 v[12:13], v[74:75], v[14:15] op_sel_hi:[1,0]
	v_pk_fma_f32 v[30:31], v[0:1], v[90:91], v[2:3] op_sel_hi:[0,1,1]
	v_lshlrev_b32_e32 v2, 16, v4
	v_and_b32_e32 v3, 0xffff0000, v4
	v_pk_fma_f32 v[32:33], v[42:43], v[32:33], v[58:59] op_sel:[0,1,0] op_sel_hi:[1,0,1]
	v_pk_fma_f32 v[10:11], v[56:57], v[10:11], v[72:73]
	v_pk_fma_f32 v[12:13], v[52:53], v[12:13], v[68:69]
	v_pk_fma_f32 v[32:33], v[0:1], v[2:3], v[32:33] op_sel_hi:[0,1,1]
	v_lshlrev_b32_e32 v2, 16, v5
	v_and_b32_e32 v3, 0xffff0000, v5
	v_pk_mul_f32 v[4:5], v[36:37], v[14:15] op_sel_hi:[1,0]
	v_pk_fma_f32 v[10:11], v[0:1], v[76:77], v[10:11] op_sel_hi:[0,1,1]
	v_pk_fma_f32 v[12:13], v[0:1], v[38:39], v[12:13] op_sel_hi:[0,1,1]
	v_pk_fma_f32 v[4:5], v[44:45], v[4:5], v[60:61] op_sel:[0,1,0] op_sel_hi:[1,0,1]
	v_cmp_lt_i32_e32 vcc, s82, v18
	v_pk_fma_f32 v[14:15], v[0:1], v[2:3], v[4:5] op_sel_hi:[0,1,1]
	v_cvt_pk_bf16_f32 v2, v6, v7
	v_cvt_pk_bf16_f32 v3, v10, v11
	v_cvt_pk_bf16_f32 v4, v8, v9
	v_cvt_pk_bf16_f32 v5, v12, v13
	global_store_dwordx4 v[28:29], v[2:5], off
	s_or_b64 s[8:9], vcc, s[8:9]
	s_nop 0
	v_cvt_pk_bf16_f32 v2, v16, v17
	v_cvt_pk_bf16_f32 v3, v30, v31
	v_cvt_pk_bf16_f32 v4, v32, v33
	v_cvt_pk_bf16_f32 v5, v14, v15
	global_store_dwordx4 v[28:29], v[2:5], off offset:16
	s_andn2_b64 exec, exec, s[8:9]
	s_cbranch_execnz .LBB0_120

; __device__ __forceinline__ unsigned pk2(float lo, float hi) { const f32x2_cv v = {lo, hi}; const bf16x2_cv b = __builtin_convertvector(v, bf16x2_cv); return __builtin_bit_cast(unsigned, b); }
; __device__ __forceinline__ float wave_sum(float v) {
; #pragma unroll
;     for (int o = 1; o < 64; o <<= 1) v += __shfl_xor(v, o);
;     return v;
; __device__ __forceinline__ void p0_prologue(ArgP ap, unsigned char* lds, int tid) {
;     ...
;         float s = 0.f;
; #pragma unroll
;         for (int j = 0; j < 4; ++j) { f32x4_t v = (f32x4_t){0.f, 0.f, 0.f, 0.f}; if (src) v = __builtin_nontemporal_load((const f32x4_t*)(src + 4 * lane + 256 * j));
;             s += v[0] * v[0] + v[1] * v[1] + v[2] * v[2] + v[3] * v[3];
;             u32x2_t w; w.x = pk2(v[0], v[1]); w.y = pk2(v[2], v[3]); *(u32x2_t*)(HB + (size_t)r * 1024 + 4 * lane + 256 * j) = w; }
;         s = wave_sum(s); if (lane == 0) ssq0[r] = s;
.LBB0_958:
	s_or_b64 exec, exec, s[12:13]
	v_mul_f32_e32 v7, v7, v7
	v_mul_f32_e32 v3, v3, v3
	v_fmac_f32_e32 v7, v6, v6
	v_fmac_f32_e32 v3, v2, v2
	v_fmac_f32_e32 v7, v8, v8
	v_fmac_f32_e32 v3, v4, v4
	v_fmac_f32_e32 v7, v9, v9
	v_fmac_f32_e32 v3, v5, v5
	v_add_f32_e32 v2, v7, v3
	v_mul_f32_e32 v3, v15, v15
	v_fmac_f32_e32 v3, v14, v14
	v_fmac_f32_e32 v3, v16, v16
	v_fmac_f32_e32 v3, v17, v17
	v_add_f32_e32 v2, v2, v3
	s_waitcnt vmcnt(0)
	v_mul_f32_e32 v3, v11, v11
	v_fmac_f32_e32 v3, v10, v10
	v_fmac_f32_e32 v3, v12, v12
	v_fmac_f32_e32 v3, v13, v13
	v_add_f32_e32 v2, v2, v3
	s_nop 1
	v_mov_b32_dpp v3, v2 quad_perm:[1,0,3,2] row_mask:0xf bank_mask:0xf
	v_cvt_pk_bf16_f32 v4, v10, v11
	v_cvt_pk_bf16_f32 v5, v12, v13
	global_store_dwordx2 v[22:23], v[4:5], off offset:512
	s_waitcnt lgkmcnt(0)
	v_add_f32_e32 v2, v2, v3
	s_nop 1
	v_mov_b32_dpp v3, v2 quad_perm:[2,3,0,1] row_mask:0xf bank_mask:0xf
	s_waitcnt lgkmcnt(0)
	v_add_f32_e32 v2, v2, v3
	s_nop 1
	v_mov_b32_dpp v3, v2 row_half_mirror row_mask:0xf bank_mask:0xf
	s_waitcnt lgkmcnt(0)
	v_add_f32_e32 v2, v2, v3
	s_nop 1
	v_mov_b32_dpp v3, v2 row_mirror row_mask:0xf bank_mask:0xf
	s_waitcnt lgkmcnt(0)
	v_add_f32_e32 v2, v2, v3
	v_mov_b32_e32 v3, v2
	s_nop 1
	v_permlane16_swap_b32_e32 v3, v2
	s_nop 1
	s_waitcnt lgkmcnt(0)
	v_add_f32_e32 v2, v2, v3
	v_mov_b32_e32 v3, v2
	s_nop 1
	v_permlane32_swap_b32_e32 v3, v2
	s_nop 1
	s_and_saveexec_b64 s[12:13], s[36:37]
	s_cbranch_execz .LBB0_933
	s_waitcnt lgkmcnt(0)
	v_add_f32_e32 v2, v2, v3
	global_store_dword v[20:21], v2, off
	s_branch .LBB0_933
